# v51 + first gla chunk item per workgroup: wait for the gate-weight loads deferred until after the raw k/v loads are issued (one load round trip instead of two)
# baseline (speedup 1.0000x reference)
; template <int MODE>
; __device__ __forceinline__ void gla_chunk_item(int item, const u16* PROJ, u16* MIXIN, const float* wgate, const float* bgate, const float* ggla, float* GS, float* GDEC, const u16* GSB, LAS unsigned char* lds, GateW& gw_) {
;     ...
;     if (h != gw_.h) {
; #pragma unroll
;         for (int r = 0; r < 16; ++r) gw_.wg[r] = wgate[r * 256 + h * 64 + d];
;         gw_.bgd = bgate[h * 64 + d]; gw_.h = h;
.LBB0_231:
	s_and_b64 vcc, exec, s[78:79]
	v_mov_b32_e32 v100, v51
	v_mov_b32_e32 v99, v50
	v_mov_b32_e32 v98, v49
	v_mov_b32_e32 v97, v48
	v_mov_b32_e32 v96, v47
	v_mov_b32_e32 v95, v46
	v_mov_b32_e32 v94, v37
	v_mov_b32_e32 v93, v36
	v_mov_b32_e32 v92, v45
	v_mov_b32_e32 v91, v44
	v_mov_b32_e32 v90, v43
	v_mov_b32_e32 v89, v42
	v_mov_b32_e32 v88, v41
	v_mov_b32_e32 v31, v40
	v_mov_b32_e32 v30, v39
	v_mov_b32_e32 v29, v38
	s_mov_b32 s35, s33
	v_mov_b32_e32 v28, v35
	s_cbranch_vccz .LBB0_234
	s_bfe_u32 s56, s50, 0x20005
	s_lshl_b32 s57, s56, 6
	s_cmp_eq_u32 s56, s33
	v_readfirstlane_b32 s55, v129
	s_cbranch_scc1 .LBB0_243
	v_or_b32_e32 v0, s57, v128
	v_lshlrev_b32_e32 v52, 2, v0
	v_lshl_add_u64 v[0:1], s[36:37], 0, v[52:53]
	v_add_co_u32_e32 v2, vcc, 0x1000, v0
	global_load_dword v24, v52, s[36:37]
	global_load_dword v26, v52, s[36:37] offset:1024
	global_load_dword v22, v52, s[36:37] offset:2048
	global_load_dword v20, v52, s[36:37] offset:3072
	v_addc_co_u32_e32 v3, vcc, 0, v1, vcc
	global_load_dword v25, v[2:3], off
	global_load_dword v27, v[2:3], off offset:1024
	global_load_dword v23, v[2:3], off offset:2048
	global_load_dword v21, v[2:3], off offset:3072
	v_add_co_u32_e32 v2, vcc, 0x2000, v0
	s_mov_b32 s35, s56
	s_nop 0
	v_addc_co_u32_e32 v3, vcc, 0, v1, vcc
	v_add_co_u32_e32 v0, vcc, 0x3000, v0
	global_load_dword v16, v[2:3], off
	global_load_dword v18, v[2:3], off offset:1024
	global_load_dword v14, v[2:3], off offset:2048
	global_load_dword v12, v[2:3], off offset:3072
	v_addc_co_u32_e32 v1, vcc, 0, v1, vcc
	global_load_dword v17, v[0:1], off
	global_load_dword v19, v[0:1], off offset:1024
	global_load_dword v15, v[0:1], off offset:2048
	global_load_dword v13, v[0:1], off offset:3072
	global_load_dword v28, v52, s[38:39]
	s_branch .LBB0_244

; #define LAS __attribute__((address_space(3)))
; __device__ __forceinline__ float bf2f(unsigned b) { return __uint_as_float(b << 16); }
; __device__ __forceinline__ float logsig(float x) { return fminf(x, 0.f) - __logf(1.f + __expf(-fabsf(x))); }
; template <int MODE>
; __device__ __forceinline__ void gla_chunk_item(int item, const u16* PROJ, u16* MIXIN, const float* wgate, const float* bgate, const float* ggla, float* GS, float* GDEC, const u16* GSB, LAS unsigned char* lds, GateW& gw_) {
;     ...
;     const int vt_ = tid >> 4, ve_ = (tid & 15) * 8;
;     u32x4 qraw, kraw, vraw0, vraw1, sraw[2];
;     if (MODE == 1) qraw = *(const u32x4*)(PROJ + (row0 + qt_) * NPROJ + C_Q + h * 64 + qd_);
;     kraw = *(const u32x4*)(PROJ + (row0 + qt_) * NPROJ + C_K + h * 64 + qd_);
;     vraw0 = *(const u32x4*)(PROJ + (row0 + vt_) * NPROJ + C_V + h * 128 + ve_);
;     vraw1 = *(const u32x4*)(PROJ + (row0 + 32 + vt_) * NPROJ + C_V + h * 128 + ve_);
;     const unsigned glr = *(const unsigned*)(PROJ + (row0 + seg * 8 + (lane >> 3)) * NPROJ + C_GLR + (lane & 7) * 2);
;     if (MODE == 1) {
; #pragma unroll
;         for (int i = 0; i < 2; ++i) sraw[i] = ((const u32x4*)(GSB + (size_t)item * 8192))[tid + 512 * i];
;     }
;     GLR[(seg * 8 + (lane >> 3)) * 16 + (lane & 7) * 2] = bf2f(glr & 0xffffu);
;     GLR[(seg * 8 + (lane >> 3)) * 16 + (lane & 7) * 2 + 1] = bf2f(glr >> 16);
;     float bl[8], run = 0.f;
; #pragma unroll
;     for (int tt = 0; tt < 8; ++tt) {
;         const LAS f32x4* gp = (const LAS f32x4*)(GLR + (seg * 8 + tt) * 16);
;         float logit = gw_.bgd;
; #pragma unroll
;         for (int r4 = 0; r4 < 4; ++r4) { const f32x4 gv = gp[r4]; logit += gv.x * gw_.wg[4 * r4] + gv.y * gw_.wg[4 * r4 + 1] + gv.z * gw_.wg[4 * r4 + 2] + gv.w * gw_.wg[4 * r4 + 3]; }
;         run += logsig(logit) * (1.f / 16.f); bl[tt] = run;
;     }
.LBB0_244:
	s_add_i32 s6, s50, 0xfffffe00
	s_lshl_b32 s58, s6, 4
	s_lshl_b32 s59, s6, 6
	s_and_b32 s58, s58, 0x3800
	s_and_b32 s59, s59, 0x7c0
	s_or_b32 s60, s58, s59
	v_add_u32_e32 v0, s60, v107
	v_mul_u32_u24_e32 v0, 0xb00, v0
	v_lshlrev_b32_e32 v52, 1, v0
	s_lshr_b32 s54, s55, 6
	v_lshl_add_u64 v[0:1], s[4:5], 0, v[52:53]
	s_lshl_b32 s58, s57, 1
	s_mov_b32 s59, s7
	v_or_b32_e32 v4, s60, v32
	v_mov_b64_e32 v[8:9], s[4:5]
	v_add_u32_e32 v10, s60, v108
	v_lshl_add_u64 v[0:1], v[0:1], 0, s[58:59]
	v_mad_u64_u32 v[4:5], s[58:59], v4, s30, v[8:9]
	s_lshl_b32 s56, s56, 8
	s_mov_b32 s57, s7
	v_mad_u64_u32 v[8:9], s[58:59], v10, s30, v[8:9]
	s_lshl_b32 s80, s54, 3
	v_lshl_add_u64 v[4:5], v[4:5], 0, s[56:57]
	v_lshlrev_b32_e32 v52, 1, v60
	v_lshl_add_u64 v[8:9], v[8:9], 0, s[56:57]
	s_add_i32 s56, s80, s60
	v_lshl_add_u64 v[4:5], v[4:5], 0, v[52:53]
	v_lshl_add_u64 v[8:9], v[8:9], 0, v[52:53]
	v_or_b32_e32 v52, s56, v34
	v_mad_u64_u32 v[102:103], s[56:57], v52, s30, v[76:77]
	global_load_dwordx4 v[8:11], v[8:9], off offset:1024
	v_mov_b32_e32 v79, v53
	global_load_dword v52, v[102:103], off offset:3072
	v_lshl_add_u64 v[0:1], v[0:1], 0, v[78:79]
	v_or_b32_e32 v79, s80, v34
	s_lshl_b32 s56, s54, 9
	v_lshl_add_u32 v79, v79, 6, v109
	s_add_i32 s56, s97, s56
	global_load_dwordx4 v[0:3], v[0:1], off offset:512
	s_or_b32 s59, s80, 3
	global_load_dwordx4 v[4:7], v[4:5], off offset:1024
	s_or_b32 s60, s80, 4
	s_or_b32 s61, s80, 5
	s_or_b32 s62, s80, 6
	s_waitcnt vmcnt(0)
	v_mov_b32_e32 v97, v24
	v_mov_b32_e32 v99, v26
	v_mov_b32_e32 v95, v22
	v_mov_b32_e32 v93, v20
	v_mov_b32_e32 v98, v25
	v_mov_b32_e32 v96, v23
	v_mov_b32_e32 v94, v21
	v_mov_b32_e32 v100, v27
	v_mov_b32_e32 v89, v16
	v_mov_b32_e32 v91, v18
	v_mov_b32_e32 v31, v14
	v_mov_b32_e32 v29, v12
	v_mov_b32_e32 v88, v15
	v_mov_b32_e32 v30, v13
	v_mov_b32_e32 v90, v17
	v_mov_b32_e32 v92, v19
	v_lshlrev_b32_e32 v102, 16, v52
	v_and_b32_e32 v103, 0xffff0000, v52
	ds_write_b64 v79, v[102:103]
	v_mov_b32_e32 v52, s56
	ds_read_b128 v[102:105], v52
	ds_read_b128 v[156:159], v52 offset:16
	ds_read_b128 v[160:163], v52 offset:32
	ds_read_b128 v[164:167], v52 offset:48
	s_mov_b32 s56, 0x3d800000
	s_waitcnt lgkmcnt(3)
	v_mul_f32_e32 v52, v103, v99
	v_fmac_f32_e32 v52, v102, v97
	v_fmac_f32_e32 v52, v104, v95
	s_waitcnt lgkmcnt(2)
	v_mul_f32_e32 v79, v157, v100
	s_waitcnt lgkmcnt(0)
	v_mov_b32_e32 v103, v164
	v_mov_b32_e32 v164, v161
	v_fmac_f32_e32 v52, v105, v93
	v_fmac_f32_e32 v79, v156, v98
	v_mov_b32_e32 v102, v160
	v_pk_mul_f32 v[104:105], v[164:165], v[18:19]
	v_fmac_f32_e32 v79, v158, v96
	v_pk_fma_f32 v[102:103], v[102:103], v[16:17], v[104:105]
	v_mov_b32_e32 v104, v162
	v_mov_b32_e32 v105, v166
	v_add_f32_e32 v52, v28, v52
	v_fmac_f32_e32 v79, v159, v94
	v_pk_fma_f32 v[102:103], v[104:105], v[14:15], v[102:103]
	v_mov_b32_e32 v166, v163
	v_add_f32_e32 v52, v52, v79
	v_pk_fma_f32 v[102:103], v[166:167], v[12:13], v[102:103]
	s_nop 0
	v_add_f32_e32 v52, v52, v102
	v_add_f32_e32 v52, v52, v103
	v_min_f32_e32 v79, 0, v52
	v_mul_f32_e64 v52, |v52|, s20
	v_exp_f32_e32 v52, v52
	s_nop 0
	v_add_f32_e32 v52, 1.0, v52
	v_cmp_gt_f32_e32 vcc, s21, v52
	s_nop 1
	v_cndmask_b32_e64 v81, 0, 32, vcc
	v_ldexp_f32 v52, v52, v81
	v_log_f32_e32 v52, v52
	s_nop 0
	v_mul_f32_e32 v81, 0x3f317217, v52
	v_fma_f32 v81, v52, s8, -v81
	v_fmac_f32_e32 v81, 0x3377d1cf, v52
	v_fmac_f32_e32 v81, 0x3f317217, v52
	v_cmp_lt_f32_e64 s[78:79], |v52|, s9
	s_nop 1
	v_cndmask_b32_e64 v52, v52, v81, s[78:79]
	v_cndmask_b32_e32 v81, 0, v152, vcc
	v_sub_f32_e32 v52, v52, v81
	v_sub_f32_e32 v52, v79, v52
	v_fma_f32 v52, v52, s56, 0
	s_or_b32 s56, s80, 1
	s_lshl_b32 s57, s56, 6
	s_add_i32 s57, s97, s57
	v_mov_b32_e32 v79, s57
	ds_read_b128 v[102:105], v79
	ds_read_b128 v[156:159], v79 offset:16
	ds_read_b128 v[160:163], v79 offset:32
	ds_read_b128 v[164:167], v79 offset:48
	s_or_b32 s57, s80, 2
	s_waitcnt lgkmcnt(3)
	v_mul_f32_e32 v79, v99, v103
	v_fmac_f32_e32 v79, v97, v102
	v_fmac_f32_e32 v79, v95, v104
	s_waitcnt lgkmcnt(2)
	v_mul_f32_e32 v81, v100, v157
	s_waitcnt lgkmcnt(0)
	v_mov_b32_e32 v103, v164
	v_mov_b32_e32 v164, v161
	v_fmac_f32_e32 v79, v93, v105
	v_fmac_f32_e32 v81, v98, v156
	v_mov_b32_e32 v102, v160
	v_pk_mul_f32 v[104:105], v[18:19], v[164:165]
	v_fmac_f32_e32 v81, v96, v158
	v_pk_fma_f32 v[102:103], v[16:17], v[102:103], v[104:105]
	v_mov_b32_e32 v104, v162
	v_mov_b32_e32 v105, v166
	v_add_f32_e32 v79, v28, v79
	v_fmac_f32_e32 v81, v94, v159
	v_pk_fma_f32 v[102:103], v[14:15], v[104:105], v[102:103]
	v_mov_b32_e32 v166, v163
	v_add_f32_e32 v79, v79, v81
	v_pk_fma_f32 v[102:103], v[12:13], v[166:167], v[102:103]
	s_lshl_b32 s58, s57, 6
	v_add_f32_e32 v79, v79, v102
	v_add_f32_e32 v79, v79, v103
	v_min_f32_e32 v81, 0, v79
	v_mul_f32_e64 v79, |v79|, s20
	v_exp_f32_e32 v79, v79
	s_add_i32 s58, s97, s58
	v_add_f32_e32 v79, 1.0, v79
	v_cmp_gt_f32_e32 vcc, s21, v79
	s_nop 1
	v_cndmask_b32_e64 v83, 0, 32, vcc
	v_ldexp_f32 v79, v79, v83
	v_log_f32_e32 v79, v79
	s_nop 0
	v_mul_f32_e32 v83, 0x3f317217, v79
	v_fma_f32 v83, v79, s8, -v83
	v_fmac_f32_e32 v83, 0x3377d1cf, v79
	v_fmac_f32_e32 v83, 0x3f317217, v79
	v_cmp_lt_f32_e64 s[78:79], |v79|, s9
	s_nop 1
	v_cndmask_b32_e64 v79, v79, v83, s[78:79]
	v_cndmask_b32_e32 v83, 0, v152, vcc
	v_sub_f32_e32 v79, v79, v83
	v_sub_f32_e32 v79, v81, v79
	v_mov_b32_e32 v81, s58
	ds_read_b128 v[102:105], v81
	ds_read_b128 v[156:159], v81 offset:16
	ds_read_b128 v[160:163], v81 offset:32
	ds_read_b128 v[164:167], v81 offset:48
	s_lshl_b32 s58, s59, 6
	s_waitcnt lgkmcnt(3)
	v_mov_b32_e32 v168, v102
	s_waitcnt lgkmcnt(2)
; #define LAS __attribute__((address_space(3)))
; __device__ __forceinline__ float logsig(float x) { return fminf(x, 0.f) - __logf(1.f + __expf(-fabsf(x))); }
; template <int MODE>
; __device__ __forceinline__ void gla_chunk_item(int item, const u16* PROJ, u16* MIXIN, const float* wgate, const float* bgate, const float* ggla, float* GS, float* GDEC, const u16* GSB, LAS unsigned char* lds, GateW& gw_) {
;     ...
;     for (int tt = 0; tt < 8; ++tt) {
;         const LAS f32x4* gp = (const LAS f32x4*)(GLR + (seg * 8 + tt) * 16);
;         float logit = gw_.bgd;
; #pragma unroll
;         for (int r4 = 0; r4 < 4; ++r4) { const f32x4 gv = gp[r4]; logit += gv.x * gw_.wg[4 * r4] + gv.y * gw_.wg[4 * r4 + 1] + gv.z * gw_.wg[4 * r4 + 2] + gv.w * gw_.wg[4 * r4 + 3]; }
;         run += logsig(logit) * (1.f / 16.f); bl[tt] = run;
;     }
	v_mov_b32_e32 v169, v156
	v_mov_b32_e32 v156, v103
	v_pk_mul_f32 v[102:103], v[26:27], v[156:157]
	v_mov_b32_e32 v156, v104
	v_pk_fma_f32 v[102:103], v[24:25], v[168:169], v[102:103]
	v_mov_b32_e32 v157, v158
	v_pk_fma_f32 v[102:103], v[22:23], v[156:157], v[102:103]
	v_mov_b32_e32 v158, v105
	v_pk_fma_f32 v[102:103], v[20:21], v[158:159], v[102:103]
	s_add_i32 s58, s97, s58
	v_add_f32_e32 v81, v28, v102
	v_add_f32_e32 v81, v81, v103
	s_waitcnt lgkmcnt(0)
	v_mov_b32_e32 v103, v164
	v_mov_b32_e32 v164, v161
	v_mov_b32_e32 v102, v160
	v_pk_mul_f32 v[104:105], v[18:19], v[164:165]
	v_fmamk_f32 v79, v79, 0x3d800000, v52
	v_pk_fma_f32 v[102:103], v[16:17], v[102:103], v[104:105]
	v_mov_b32_e32 v104, v162
	v_mov_b32_e32 v105, v166
	v_pk_fma_f32 v[102:103], v[14:15], v[104:105], v[102:103]
	v_mov_b32_e32 v166, v163
	v_pk_fma_f32 v[102:103], v[12:13], v[166:167], v[102:103]
	s_nop 0
	v_add_f32_e32 v81, v81, v102
	v_add_f32_e32 v81, v81, v103
	v_min_f32_e32 v83, 0, v81
	v_mul_f32_e64 v81, |v81|, s20
	v_exp_f32_e32 v81, v81
	s_nop 0
	v_add_f32_e32 v81, 1.0, v81
	v_cmp_gt_f32_e32 vcc, s21, v81
	s_nop 1
	v_cndmask_b32_e64 v85, 0, 32, vcc
	v_ldexp_f32 v81, v81, v85
	v_log_f32_e32 v81, v81
	s_nop 0
	v_mul_f32_e32 v85, 0x3f317217, v81
	v_fma_f32 v85, v81, s8, -v85
	v_fmac_f32_e32 v85, 0x3377d1cf, v81
	v_fmac_f32_e32 v85, 0x3f317217, v81
	v_cmp_lt_f32_e64 s[78:79], |v81|, s9
	s_nop 1
	v_cndmask_b32_e64 v81, v81, v85, s[78:79]
	v_cndmask_b32_e32 v85, 0, v152, vcc
	v_sub_f32_e32 v81, v81, v85
	v_sub_f32_e32 v81, v83, v81
	v_mov_b32_e32 v83, s58
	ds_read_b128 v[102:105], v83
	ds_read_b128 v[156:159], v83 offset:16
	ds_read_b128 v[160:163], v83 offset:32
	ds_read_b128 v[164:167], v83 offset:48
	s_lshl_b32 s58, s60, 6
	s_waitcnt lgkmcnt(3)
	v_mov_b32_e32 v168, v102
	s_waitcnt lgkmcnt(2)
	v_mov_b32_e32 v169, v156
	v_mov_b32_e32 v156, v103
	v_pk_mul_f32 v[102:103], v[26:27], v[156:157]
	v_mov_b32_e32 v156, v104
	v_pk_fma_f32 v[102:103], v[24:25], v[168:169], v[102:103]
	v_mov_b32_e32 v157, v158
	v_pk_fma_f32 v[102:103], v[22:23], v[156:157], v[102:103]
	v_mov_b32_e32 v158, v105
	v_pk_fma_f32 v[102:103], v[20:21], v[158:159], v[102:103]
	s_add_i32 s58, s97, s58
	v_add_f32_e32 v83, v28, v102
	v_add_f32_e32 v83, v83, v103
	s_waitcnt lgkmcnt(0)
	v_mov_b32_e32 v103, v164
	v_mov_b32_e32 v164, v161
	v_mov_b32_e32 v102, v160
	v_pk_mul_f32 v[104:105], v[18:19], v[164:165]
	v_fmamk_f32 v81, v81, 0x3d800000, v79
	v_pk_fma_f32 v[102:103], v[16:17], v[102:103], v[104:105]
	v_mov_b32_e32 v104, v162
	v_mov_b32_e32 v105, v166
	v_pk_fma_f32 v[102:103], v[14:15], v[104:105], v[102:103]
	v_mov_b32_e32 v166, v163
	v_pk_fma_f32 v[102:103], v[12:13], v[166:167], v[102:103]
	s_nop 0
	v_add_f32_e32 v83, v83, v102
	v_add_f32_e32 v83, v83, v103
	v_min_f32_e32 v85, 0, v83
	v_mul_f32_e64 v83, |v83|, s20
	v_exp_f32_e32 v83, v83
	s_nop 0
	v_add_f32_e32 v83, 1.0, v83
	v_cmp_gt_f32_e32 vcc, s21, v83
	s_nop 1
	v_cndmask_b32_e64 v87, 0, 32, vcc
	v_ldexp_f32 v83, v83, v87
	v_log_f32_e32 v83, v83
	s_nop 0
	v_mul_f32_e32 v87, 0x3f317217, v83
	v_fma_f32 v87, v83, s8, -v87
	v_fmac_f32_e32 v87, 0x3377d1cf, v83
	v_fmac_f32_e32 v87, 0x3f317217, v83
	v_cmp_lt_f32_e64 s[78:79], |v83|, s9
	s_nop 1
	v_cndmask_b32_e64 v83, v83, v87, s[78:79]
	v_cndmask_b32_e32 v87, 0, v152, vcc
	v_sub_f32_e32 v83, v83, v87
	v_sub_f32_e32 v83, v85, v83
	v_mov_b32_e32 v85, s58
	ds_read_b128 v[102:105], v85
	ds_read_b128 v[156:159], v85 offset:16
	ds_read_b128 v[160:163], v85 offset:32
	ds_read_b128 v[164:167], v85 offset:48
	s_lshl_b32 s58, s61, 6
	s_waitcnt lgkmcnt(3)
	v_mov_b32_e32 v168, v102
	s_waitcnt lgkmcnt(2)
	v_mov_b32_e32 v169, v156
	v_mov_b32_e32 v156, v103
	v_pk_mul_f32 v[102:103], v[26:27], v[156:157]
	v_mov_b32_e32 v156, v104
	v_pk_fma_f32 v[102:103], v[24:25], v[168:169], v[102:103]
	v_mov_b32_e32 v157, v158
	v_pk_fma_f32 v[102:103], v[22:23], v[156:157], v[102:103]
	v_mov_b32_e32 v158, v105
	v_pk_fma_f32 v[102:103], v[20:21], v[158:159], v[102:103]
	s_add_i32 s58, s97, s58
	v_add_f32_e32 v85, v28, v102
	v_add_f32_e32 v85, v85, v103
	s_waitcnt lgkmcnt(0)
	v_mov_b32_e32 v103, v164
	v_mov_b32_e32 v164, v161
	v_mov_b32_e32 v102, v160
	v_pk_mul_f32 v[104:105], v[18:19], v[164:165]
	v_fmamk_f32 v83, v83, 0x3d800000, v81
	v_pk_fma_f32 v[102:103], v[16:17], v[102:103], v[104:105]
	v_mov_b32_e32 v104, v162
	v_mov_b32_e32 v105, v166
	v_pk_fma_f32 v[102:103], v[14:15], v[104:105], v[102:103]
	v_mov_b32_e32 v166, v163
	v_pk_fma_f32 v[102:103], v[12:13], v[166:167], v[102:103]
	s_nop 0
	v_add_f32_e32 v85, v85, v102
	v_add_f32_e32 v85, v85, v103
	v_min_f32_e32 v87, 0, v85
	v_mul_f32_e64 v85, |v85|, s20
	v_exp_f32_e32 v85, v85
	s_nop 0
	v_add_f32_e32 v85, 1.0, v85
	v_cmp_gt_f32_e32 vcc, s21, v85
	s_nop 1
	v_cndmask_b32_e64 v101, 0, 32, vcc
	v_ldexp_f32 v85, v85, v101
	v_log_f32_e32 v85, v85
	s_nop 0
	v_mul_f32_e32 v101, 0x3f317217, v85
	v_fma_f32 v101, v85, s8, -v101
	v_fmac_f32_e32 v101, 0x3377d1cf, v85
	v_fmac_f32_e32 v101, 0x3f317217, v85
	v_cmp_lt_f32_e64 s[78:79], |v85|, s9
	s_nop 1
	v_cndmask_b32_e64 v85, v85, v101, s[78:79]
	v_cndmask_b32_e32 v101, 0, v152, vcc
	v_sub_f32_e32 v85, v85, v101
	v_sub_f32_e32 v85, v87, v85
	v_mov_b32_e32 v87, s58
	ds_read_b128 v[102:105], v87
	ds_read_b128 v[156:159], v87 offset:16
	ds_read_b128 v[160:163], v87 offset:32
	ds_read_b128 v[164:167], v87 offset:48
	s_lshl_b32 s58, s62, 6
	s_waitcnt lgkmcnt(3)
	v_mov_b32_e32 v168, v102
	s_waitcnt lgkmcnt(2)
	v_mov_b32_e32 v169, v156
	v_mov_b32_e32 v156, v103
	v_pk_mul_f32 v[102:103], v[26:27], v[156:157]
	v_mov_b32_e32 v156, v104
	v_pk_fma_f32 v[102:103], v[24:25], v[168:169], v[102:103]
	v_mov_b32_e32 v157, v158
	v_pk_fma_f32 v[102:103], v[22:23], v[156:157], v[102:103]
	v_mov_b32_e32 v158, v105
	v_pk_fma_f32 v[102:103], v[20:21], v[158:159], v[102:103]
	s_add_i32 s58, s97, s58
	v_add_f32_e32 v87, v28, v102
	v_add_f32_e32 v87, v87, v103
	s_waitcnt lgkmcnt(0)
; #define LAS __attribute__((address_space(3)))
; __device__ __forceinline__ float logsig(float x) { return fminf(x, 0.f) - __logf(1.f + __expf(-fabsf(x))); }
; #define LBAR() do { asm volatile("s_waitcnt lgkmcnt(0)" ::: "memory"); __builtin_amdgcn_s_barrier(); asm volatile("" ::: "memory"); } while (0)
; template <int MODE>
; __device__ __forceinline__ void gla_chunk_item(int item, const u16* PROJ, u16* MIXIN, const float* wgate, const float* bgate, const float* ggla, float* GS, float* GDEC, const u16* GSB, LAS unsigned char* lds, GateW& gw_) {
;     ...
;         float logit = gw_.bgd;
; #pragma unroll
;         for (int r4 = 0; r4 < 4; ++r4) { const f32x4 gv = gp[r4]; logit += gv.x * gw_.wg[4 * r4] + gv.y * gw_.wg[4 * r4 + 1] + gv.z * gw_.wg[4 * r4 + 2] + gv.w * gw_.wg[4 * r4 + 3]; }
;         run += logsig(logit) * (1.f / 16.f); bl[tt] = run;
;     }
;     SEG[seg * 64 + d] = run;
;     if (MODE == 1) *(LAS u32x4*)(RQ + qt_ * 64 + qd_) = qraw;
;     *(LAS u32x4*)(RK + qt_ * 64 + qd_) = kraw;
;     *(LAS u32x2*)(RV + vt_ * RP + ve_) = (u32x2){vraw0.x, vraw0.y}; *(LAS u32x2*)(RV + vt_ * RP + ve_ + 4) = (u32x2){vraw0.z, vraw0.w};
;     *(LAS u32x2*)(RV + (32 + vt_) * RP + ve_) = (u32x2){vraw1.x, vraw1.y}; *(LAS u32x2*)(RV + (32 + vt_) * RP + ve_ + 4) = (u32x2){vraw1.z, vraw1.w};
;     if (MODE == 1) {
; #pragma unroll
;         for (int i = 0; i < 2; ++i) { const int idx = tid + 512 * i; LAS u16* sp_ = SN + (idx >> 4) * RP + (idx & 15) * 8;
;             *(LAS u32x2*)sp_ = (u32x2){sraw[i].x, sraw[i].y}; *(LAS u32x2*)(sp_ + 4) = (u32x2){sraw[i].z, sraw[i].w}; }
;     }
;     LBAR();
	v_mov_b32_e32 v103, v164
	v_mov_b32_e32 v164, v161
	v_mov_b32_e32 v102, v160
	v_pk_mul_f32 v[104:105], v[18:19], v[164:165]
	v_fmamk_f32 v85, v85, 0x3d800000, v83
	v_pk_fma_f32 v[102:103], v[16:17], v[102:103], v[104:105]
	v_mov_b32_e32 v104, v162
	v_mov_b32_e32 v105, v166
	v_pk_fma_f32 v[102:103], v[14:15], v[104:105], v[102:103]
	v_mov_b32_e32 v166, v163
	v_pk_fma_f32 v[102:103], v[12:13], v[166:167], v[102:103]
	s_nop 0
	v_add_f32_e32 v87, v87, v102
	v_add_f32_e32 v87, v87, v103
	v_min_f32_e32 v101, 0, v87
	v_mul_f32_e64 v87, |v87|, s20
	v_exp_f32_e32 v87, v87
	s_nop 0
	v_add_f32_e32 v87, 1.0, v87
	v_cmp_gt_f32_e32 vcc, s21, v87
	s_nop 1
	v_cndmask_b32_e64 v102, 0, 32, vcc
	v_ldexp_f32 v87, v87, v102
	v_log_f32_e32 v87, v87
	s_nop 0
	v_mul_f32_e32 v102, 0x3f317217, v87
	v_fma_f32 v102, v87, s8, -v102
	v_fmac_f32_e32 v102, 0x3377d1cf, v87
	v_fmac_f32_e32 v102, 0x3f317217, v87
	v_cmp_lt_f32_e64 s[78:79], |v87|, s9
	s_nop 1
	v_cndmask_b32_e64 v87, v87, v102, s[78:79]
	v_cndmask_b32_e32 v102, 0, v152, vcc
	v_sub_f32_e32 v87, v87, v102
	v_sub_f32_e32 v87, v101, v87
	v_mov_b32_e32 v101, s58
	ds_read_b128 v[102:105], v101
	ds_read_b128 v[156:159], v101 offset:16
	ds_read_b128 v[160:163], v101 offset:32
	ds_read_b128 v[164:167], v101 offset:48
	s_or_b32 s58, s80, 7
	s_waitcnt lgkmcnt(3)
	v_mov_b32_e32 v168, v102
	s_waitcnt lgkmcnt(2)
	v_mov_b32_e32 v169, v156
	v_mov_b32_e32 v156, v103
	v_pk_mul_f32 v[26:27], v[26:27], v[156:157]
	s_lshl_b32 s63, s58, 6
	v_pk_fma_f32 v[24:25], v[24:25], v[168:169], v[26:27]
	v_mov_b32_e32 v26, v104
	v_mov_b32_e32 v27, v158
	v_pk_fma_f32 v[22:23], v[22:23], v[26:27], v[24:25]
	v_mov_b32_e32 v158, v105
	v_pk_fma_f32 v[20:21], v[20:21], v[158:159], v[22:23]
	s_add_i32 s63, s97, s63
	v_add_f32_e32 v20, v28, v20
	v_add_f32_e32 v24, v20, v21
	s_waitcnt lgkmcnt(0)
	v_mov_b32_e32 v21, v164
	v_mov_b32_e32 v164, v161
	v_mov_b32_e32 v20, v160
	v_pk_mul_f32 v[22:23], v[18:19], v[164:165]
	v_mov_b32_e32 v155, s63
	v_pk_fma_f32 v[20:21], v[16:17], v[20:21], v[22:23]
	v_mov_b32_e32 v22, v162
	v_mov_b32_e32 v23, v166
	v_pk_fma_f32 v[20:21], v[14:15], v[22:23], v[20:21]
	v_mov_b32_e32 v166, v163
	v_pk_fma_f32 v[20:21], v[12:13], v[166:167], v[20:21]
	v_fmamk_f32 v87, v87, 0x3d800000, v85
	v_add_f32_e32 v20, v24, v20
	v_add_f32_e32 v20, v20, v21
	v_min_f32_e32 v21, 0, v20
	v_mul_f32_e64 v20, |v20|, s20
	v_exp_f32_e32 v20, v20
	s_and_b32 s63, s55, 0x3fffffc0
	s_cmp_gt_u32 s55, 63
	v_add_f32_e32 v20, 1.0, v20
	v_cmp_gt_f32_e32 vcc, s21, v20
	s_nop 1
	v_cndmask_b32_e64 v22, 0, 32, vcc
	v_ldexp_f32 v20, v20, v22
	v_log_f32_e32 v20, v20
	s_nop 0
	v_mul_f32_e32 v22, 0x3f317217, v20
	v_fma_f32 v22, v20, s8, -v22
	v_fmac_f32_e32 v22, 0x3377d1cf, v20
	v_fmac_f32_e32 v22, 0x3f317217, v20
	v_cmp_lt_f32_e64 s[78:79], |v20|, s9
	s_nop 1
	v_cndmask_b32_e64 v20, v20, v22, s[78:79]
	v_cndmask_b32_e32 v22, 0, v152, vcc
	v_sub_f32_e32 v20, v20, v22
	v_sub_f32_e32 v101, v21, v20
	ds_read_b128 v[20:23], v155
	ds_read_b128 v[24:27], v155 offset:16
	ds_read_b128 v[102:105], v155 offset:32
	ds_read_b128 v[156:159], v155 offset:48
	s_waitcnt lgkmcnt(3)
	v_mul_f32_e32 v21, v99, v21
	v_fmac_f32_e32 v21, v97, v20
	v_fmac_f32_e32 v21, v95, v22
	v_fmac_f32_e32 v21, v93, v23
	v_add_f32_e32 v20, v28, v21
	s_waitcnt lgkmcnt(2)
	v_mul_f32_e32 v21, v100, v25
	v_fmac_f32_e32 v21, v98, v24
	v_fmac_f32_e32 v21, v96, v26
	v_fmac_f32_e32 v21, v94, v27
	v_add_f32_e32 v22, v20, v21
	s_waitcnt lgkmcnt(0)
	v_mov_b32_e32 v21, v156
	v_mov_b32_e32 v156, v103
	v_mov_b32_e32 v20, v102
	v_pk_mul_f32 v[18:19], v[18:19], v[156:157]
	s_nop 0
	v_pk_fma_f32 v[16:17], v[16:17], v[20:21], v[18:19]
	v_mov_b32_e32 v18, v104
	v_mov_b32_e32 v19, v158
	v_pk_fma_f32 v[14:15], v[14:15], v[18:19], v[16:17]
	v_mov_b32_e32 v158, v105
	v_pk_fma_f32 v[12:13], v[12:13], v[158:159], v[14:15]
	v_fmamk_f32 v15, v101, 0x3d800000, v87
	v_add_f32_e32 v12, v22, v12
	v_add_f32_e32 v12, v12, v13
	v_min_f32_e32 v13, 0, v12
	v_mul_f32_e64 v12, |v12|, s20
	v_exp_f32_e32 v12, v12
	v_lshl_add_u32 v16, s54, 10, v112
	v_lshl_add_u32 v17, s56, 7, v112
	v_lshl_add_u32 v18, s57, 7, v112
	v_add_f32_e32 v12, 1.0, v12
	v_cmp_gt_f32_e32 vcc, s21, v12
	v_lshl_add_u32 v19, s59, 7, v112
	v_lshl_add_u32 v20, s60, 7, v112
	v_cndmask_b32_e64 v14, 0, 32, vcc
	v_ldexp_f32 v12, v12, v14
	v_log_f32_e32 v12, v12
	v_lshl_add_u32 v21, s61, 7, v112
	v_lshl_add_u32 v22, s62, 7, v112
	v_mul_f32_e32 v14, 0x3f317217, v12
	v_fma_f32 v14, v12, s8, -v14
	v_fmac_f32_e32 v14, 0x3377d1cf, v12
	v_fmac_f32_e32 v14, 0x3f317217, v12
	v_cmp_lt_f32_e64 s[78:79], |v12|, s9
	s_nop 1
	v_cndmask_b32_e64 v12, v12, v14, s[78:79]
	v_cndmask_b32_e32 v14, 0, v152, vcc
	v_sub_f32_e32 v12, v12, v14
	v_sub_f32_e32 v12, v13, v12
	v_lshl_add_u32 v13, s63, 2, v33
	v_fmamk_f32 v12, v12, 0x3d800000, v15
	ds_write_b32 v13, v12
	ds_write_b128 v110, v[0:3] offset:45056
	v_add_u32_e32 v0, 0xd000, v111
	ds_write2_b64 v0, v[4:5], v[6:7] offset1:1
	v_add_u32_e32 v0, 0xf100, v111
	ds_write2_b64 v0, v[8:9], v[10:11] offset1:1
	s_waitcnt lgkmcnt(0)
	s_barrier
; #define LAS __attribute__((address_space(3)))
; __device__ __forceinline__ float bf2f(unsigned b) { return __uint_as_float(b << 16); }
; __device__ __forceinline__ unsigned pk2(float lo, float hi) { unsigned r; asm("v_cvt_pk_bf16_f32 %0, %1, %2" : "=v"(r) : "v"(lo), "v"(hi)); return r; }
; template <int MODE>
; __device__ __forceinline__ void gla_chunk_item(int item, const u16* PROJ, u16* MIXIN, const float* wgate, const float* bgate, const float* ggla, float* GS, float* GDEC, const u16* GSB, LAS unsigned char* lds, GateW& gw_) {
;     ...
;     float off = 0.f, tot = 0.f;
; #pragma unroll
;     for (int s = 0; s < 8; ++s) { const float v = SEG[s * 64 + d]; tot += v; off += (s < seg) ? v : 0.f; }
;     if (MODE == 0) {
;         float kd[8];
; #pragma unroll
;         for (int tt = 0; tt < 8; ++tt) kd[tt] = bf2f(RK[(seg * 8 + tt) * 64 + d]) * __expf(tot - (off + bl[tt]));
;         u32x4 kk; kk.x = pk2(kd[0], kd[1]); kk.y = pk2(kd[2], kd[3]); kk.z = pk2(kd[4], kd[5]); kk.w = pk2(kd[6], kd[7]);
;         *(LAS u32x4*)(KdT + d * LD + seg * 8) = kk;
;         if (seg == 0) GDEC[(size_t)item * 64 + d] = __expf(tot);
	ds_read2st64_b32 v[0:1], v33 offset1:1
	s_cselect_b64 vcc, -1, 0
	s_cmpk_gt_u32 s55, 0x7f
	s_cselect_b64 s[90:91], -1, 0
	s_cmpk_gt_u32 s55, 0xbf
	s_waitcnt lgkmcnt(0)
	v_add_f32_e32 v0, 0, v0
	v_cndmask_b32_e32 v2, 0, v0, vcc
	v_add_f32_e32 v3, v0, v1
	v_cndmask_b32_e64 v0, 0, v1, s[90:91]
	v_add_f32_e32 v2, v2, v0
	ds_read2st64_b32 v[0:1], v33 offset0:2 offset1:3
	s_cselect_b64 s[88:89], -1, 0
	s_cmpk_gt_u32 s55, 0xff
	s_cselect_b64 s[86:87], -1, 0
	s_cmpk_gt_u32 s55, 0x13f
	s_waitcnt lgkmcnt(0)
	v_add_f32_e32 v3, v3, v0
	v_cndmask_b32_e64 v0, 0, v0, s[88:89]
	v_add_f32_e32 v0, v2, v0
	v_add_f32_e32 v2, v3, v1
	v_cndmask_b32_e64 v1, 0, v1, s[86:87]
	v_add_f32_e32 v3, v0, v1
	ds_read2st64_b32 v[0:1], v33 offset0:4 offset1:5
	s_cselect_b64 s[84:85], -1, 0
	s_cmpk_gt_u32 s55, 0x17f
	s_cselect_b64 s[82:83], -1, 0
	s_cmpk_gt_u32 s55, 0x1bf
	s_waitcnt lgkmcnt(0)
	v_add_f32_e32 v2, v2, v0
	v_cndmask_b32_e64 v0, 0, v0, s[84:85]
	v_add_f32_e32 v0, v3, v0
	v_add_f32_e32 v2, v2, v1
	v_cndmask_b32_e64 v1, 0, v1, s[82:83]
	v_add_f32_e32 v3, v0, v1
	ds_read2st64_b32 v[0:1], v33 offset0:6 offset1:7
	s_cselect_b64 s[80:81], -1, 0
	s_cmpk_gt_u32 s55, 0x1ff
	s_cselect_b64 s[78:79], -1, 0
	s_and_b64 vcc, exec, vcc
	s_waitcnt lgkmcnt(0)
	v_add_f32_e32 v14, v2, v0
	v_cndmask_b32_e64 v0, 0, v0, s[80:81]
	v_add_f32_e32 v0, v3, v0
	v_cndmask_b32_e64 v2, 0, v1, s[78:79]
	v_add_f32_e32 v3, v0, v2
	ds_read_u16 v0, v16 offset:45056
	v_mov_b32_e32 v2, v1
	v_add_f32_e32 v5, v52, v3
	v_add_f32_e32 v6, v81, v3
	v_add_f32_e32 v7, v83, v3
	s_waitcnt lgkmcnt(0)
	v_lshlrev_b32_e32 v4, 16, v0
	v_pk_add_f32 v[0:1], v[14:15], v[2:3]
	v_add_f32_e32 v8, v85, v3
	v_sub_f32_e32 v2, v0, v5
	v_mul_f32_e32 v2, 0x3fb8aa3b, v2
	v_exp_f32_e32 v2, v2
	v_add_f32_e32 v5, v79, v3
	v_sub_f32_e32 v5, v0, v5
	v_mul_f32_e32 v5, 0x3fb8aa3b, v5
	v_mul_f32_e32 v2, v2, v4
	ds_read_u16 v4, v17 offset:45056
	v_exp_f32_e32 v5, v5
	v_sub_f32_e32 v6, v0, v6
	v_mul_f32_e32 v6, 0x3fb8aa3b, v6
	v_exp_f32_e32 v6, v6
	s_waitcnt lgkmcnt(0)
	v_lshlrev_b32_e32 v4, 16, v4
	v_mul_f32_e32 v4, v5, v4
	ds_read_u16 v5, v18 offset:45056
	v_sub_f32_e32 v7, v0, v7
	v_mul_f32_e32 v7, 0x3fb8aa3b, v7
	v_exp_f32_e32 v7, v7
	v_sub_f32_e32 v8, v0, v8
	s_waitcnt lgkmcnt(0)
	v_lshlrev_b32_e32 v5, 16, v5
	v_mul_f32_e32 v5, v6, v5
	ds_read_u16 v6, v19 offset:45056
	v_mul_f32_e32 v8, 0x3fb8aa3b, v8
	v_exp_f32_e32 v8, v8
	v_add_f32_e32 v9, v87, v3
	v_sub_f32_e32 v9, v0, v9
	s_waitcnt lgkmcnt(0)
	v_lshlrev_b32_e32 v6, 16, v6
	v_mul_f32_e32 v6, v7, v6
	ds_read_u16 v7, v20 offset:45056
	v_mul_f32_e32 v9, 0x3fb8aa3b, v9
	v_exp_f32_e32 v9, v9
	v_sub_f32_e32 v1, v0, v1
	v_mul_f32_e32 v1, 0x3fb8aa3b, v1
	s_waitcnt lgkmcnt(0)
	v_lshlrev_b32_e32 v7, 16, v7
	v_mul_f32_e32 v7, v8, v7
	ds_read_u16 v8, v21 offset:45056
	v_exp_f32_e32 v1, v1
	v_add_f32_e32 v3, v12, v3
	v_sub_f32_e32 v3, v0, v3
	v_mul_f32_e32 v3, 0x3fb8aa3b, v3
	s_waitcnt lgkmcnt(0)
	v_lshlrev_b32_e32 v8, 16, v8
	v_mul_f32_e32 v8, v9, v8
	ds_read_u16 v9, v22 offset:45056
	v_exp_f32_e32 v3, v3
	v_cvt_pk_bf16_f32 v2, v2, v4
	v_cvt_pk_bf16_f32 v4, v7, v8
	s_waitcnt lgkmcnt(0)
	v_lshlrev_b32_e32 v9, 16, v9
	v_mul_f32_e32 v1, v1, v9
	v_lshl_add_u32 v9, s58, 7, v112
	ds_read_u16 v9, v9 offset:45056
	s_waitcnt lgkmcnt(0)
	v_lshlrev_b32_e32 v9, 16, v9
	v_mul_f32_e32 v9, v3, v9
	v_cvt_pk_bf16_f32 v3, v5, v6
	v_cvt_pk_bf16_f32 v5, v1, v9
	v_lshl_add_u32 v1, s54, 4, v113
	ds_write_b128 v1, v[2:5] offset:18432
	s_cbranch_vccnz .LBB0_246
	v_mul_f32_e32 v0, 0x3fb8aa3b, v0
	v_exp_f32_e32 v2, v0
	s_lshl_b64 s[56:57], s[6:7], 8
	v_lshl_add_u64 v[0:1], v[62:63], 0, s[56:57]
	global_store_dword v[0:1], v2, off
